# grid barrier: 17th local arriver starts an un-waited L2 write-back so the leader's write-back finds most lines clean
# speedup vs baseline: 1.0107x; 1.0021x over previous
.Lxb0_194:
	s_or_b64 exec, exec, s[12:13]
	v_cvt_f32_u32_e32 v4, v2
	s_waitcnt vmcnt(0)
	v_readfirstlane_b32 s0, v3
	v_sub_u32_e32 v3, 0, v2
	v_rcp_iflag_f32_e32 v4, v4
	v_add_u32_e32 v5, s0, v1
	v_mul_f32_e32 v4, 0x4f7ffffe, v4
	v_cvt_u32_f32_e32 v4, v4
	v_mul_lo_u32 v1, v3, v4
	v_mul_hi_u32 v1, v4, v1
	v_add_u32_e32 v1, v4, v1
	v_mul_hi_u32 v1, v5, v1
	v_mul_lo_u32 v3, v1, v2
	v_sub_u32_e32 v3, v5, v3
	v_add_u32_e32 v4, 1, v1
	v_cmp_ge_u32_e32 vcc, v3, v2
	s_nop 1
	v_cndmask_b32_e32 v1, v1, v4, vcc
	v_sub_u32_e32 v4, v3, v2
	v_cndmask_b32_e32 v3, v3, v4, vcc
	v_add_u32_e32 v4, 1, v1
	v_cmp_ge_u32_e32 vcc, v3, v2
	v_add_u32_e32 v3, 1, v5
	s_nop 0
	v_cndmask_b32_e32 v1, v1, v4, vcc
	v_mul_lo_u32 v4, v2, v1
	v_add_u32_e32 v2, v4, v2
	v_sub_u32_e32 v4, v5, v4
	v_cmp_eq_u32_e32 vcc, 16, v4
	s_cbranch_vccz .Lefl_0
	buffer_wbl2 sc1
.Lefl_0:
	v_cmp_ne_u32_e32 vcc, v3, v2
	s_and_saveexec_b64 s[0:1], vcc
	s_xor_b64 s[10:11], exec, s[0:1]
	s_cbranch_execz .Lxb0_208
	s_waitcnt lgkmcnt(0)
	buffer_inv sc1
	v_mov_b32_e32 v0, 0x2000
	global_load_dword v0, v0, s[8:9] offset:1024 sc1
	s_add_u32 s16, s8, 0x2400
	s_addc_u32 s17, s9, 0
	s_waitcnt vmcnt(0)
	v_cmp_eq_u32_e32 vcc, v0, v1
	s_and_saveexec_b64 s[12:13], vcc
	s_cbranch_execz .Lxb0_207
	s_add_u32 s14, s54, 0x4200
	s_addc_u32 s15, s55, 0
	s_mov_b32 s0, 1
	s_mov_b64 s[20:21], 0
	v_mov_b32_e32 v0, 0
	s_branch .Lxb0_198

.Lefl_2:
	v_cmp_ne_u32_e32 vcc, v3, v2
	s_and_saveexec_b64 s[0:1], vcc
	s_xor_b64 s[10:11], exec, s[0:1]
	s_cbranch_execz .LBB0_270
	s_waitcnt lgkmcnt(0)
	buffer_inv sc1
	v_mov_b32_e32 v0, 0x2000
	global_load_dword v0, v0, s[6:7] offset:1024 sc1
	s_add_u32 s16, s6, 0x2400
	s_addc_u32 s17, s7, 0
	s_waitcnt vmcnt(0)
	v_cmp_eq_u32_e32 vcc, v0, v1
	s_and_saveexec_b64 s[12:13], vcc
	s_cbranch_execz .LBB0_269
	s_add_u32 s14, s54, 0x4200
	s_addc_u32 s15, s55, 0
	s_mov_b32 s0, 1
	s_mov_b64 s[18:19], 0
	v_mov_b32_e32 v0, 0
	s_branch .LBB0_260

.Lefl_3:
	v_cmp_ne_u32_e32 vcc, v3, v2
	s_and_saveexec_b64 s[0:1], vcc
	s_xor_b64 s[10:11], exec, s[0:1]
	s_cbranch_execz .LBB0_345
	s_waitcnt lgkmcnt(0)
	buffer_inv sc1
	v_mov_b32_e32 v0, 0x2000
	global_load_dword v0, v0, s[8:9] offset:1024 sc1
	s_add_u32 s16, s8, 0x2400
	s_addc_u32 s17, s9, 0
	s_waitcnt vmcnt(0)
	v_cmp_eq_u32_e32 vcc, v0, v1
	s_and_saveexec_b64 s[12:13], vcc
	s_cbranch_execz .LBB0_344
	s_add_u32 s14, s54, 0x4200
	s_addc_u32 s15, s55, 0
	s_mov_b32 s0, 1
	s_mov_b64 s[18:19], 0
	v_mov_b32_e32 v0, 0
	s_branch .LBB0_335

.LBB0_735:
	s_or_b64 exec, exec, s[14:15]
	v_cvt_f32_u32_e32 v4, v2
	s_waitcnt vmcnt(0)
	v_readfirstlane_b32 s0, v3
	v_sub_u32_e32 v3, 0, v2
	v_rcp_iflag_f32_e32 v4, v4
	v_add_u32_e32 v5, s0, v1
	v_mul_f32_e32 v4, 0x4f7ffffe, v4
	v_cvt_u32_f32_e32 v4, v4
	v_mul_lo_u32 v1, v3, v4
	v_mul_hi_u32 v1, v4, v1
	v_add_u32_e32 v1, v4, v1
	v_mul_hi_u32 v1, v5, v1
	v_mul_lo_u32 v3, v1, v2
	v_sub_u32_e32 v3, v5, v3
	v_add_u32_e32 v4, 1, v1
	v_cmp_ge_u32_e32 vcc, v3, v2
	s_nop 1
	v_cndmask_b32_e32 v1, v1, v4, vcc
	v_sub_u32_e32 v4, v3, v2
	v_cndmask_b32_e32 v3, v3, v4, vcc
	v_add_u32_e32 v4, 1, v1
	v_cmp_ge_u32_e32 vcc, v3, v2
	v_add_u32_e32 v3, 1, v5
	s_nop 0
	v_cndmask_b32_e32 v1, v1, v4, vcc
	v_mul_lo_u32 v4, v2, v1
	v_add_u32_e32 v2, v4, v2
	v_sub_u32_e32 v4, v5, v4
	v_cmp_eq_u32_e32 vcc, 16, v4
	s_cbranch_vccz .Lefl_7
	buffer_wbl2 sc1
.Lefl_7:
	v_cmp_ne_u32_e32 vcc, v3, v2
	s_and_saveexec_b64 s[0:1], vcc
	s_xor_b64 s[12:13], exec, s[0:1]
	s_cbranch_execz .LBB0_749
	s_waitcnt lgkmcnt(0)
	buffer_inv sc1
	v_mov_b32_e32 v0, 0x2000
	global_load_dword v0, v0, s[10:11] offset:1024 sc1
	s_add_u32 s18, s10, 0x2400
	s_addc_u32 s19, s11, 0
	s_waitcnt vmcnt(0)
	v_cmp_eq_u32_e32 vcc, v0, v1
	s_and_saveexec_b64 s[14:15], vcc
	s_cbranch_execz .LBB0_748
	s_add_u32 s16, s54, 0x4200
	s_addc_u32 s17, s55, 0
	s_mov_b32 s0, 1
	s_mov_b64 s[20:21], 0
	v_mov_b32_e32 v0, 0
	s_branch .LBB0_739

.LBB0_1040:
	s_or_b64 exec, exec, s[10:11]
	v_cvt_f32_u32_e32 v4, v2
	s_waitcnt vmcnt(0)
	v_readfirstlane_b32 s3, v3
	v_sub_u32_e32 v3, 0, v2
	v_rcp_iflag_f32_e32 v4, v4
	v_add_u32_e32 v5, s3, v1
	v_mul_f32_e32 v4, 0x4f7ffffe, v4
	v_cvt_u32_f32_e32 v4, v4
	v_mul_lo_u32 v1, v3, v4
	v_mul_hi_u32 v1, v4, v1
	v_add_u32_e32 v1, v4, v1
	v_mul_hi_u32 v1, v5, v1
	v_mul_lo_u32 v3, v1, v2
	v_sub_u32_e32 v3, v5, v3
	v_add_u32_e32 v4, 1, v1
	v_cmp_ge_u32_e32 vcc, v3, v2
	s_nop 1
	v_cndmask_b32_e32 v1, v1, v4, vcc
	v_sub_u32_e32 v4, v3, v2
	v_cndmask_b32_e32 v3, v3, v4, vcc
	v_add_u32_e32 v4, 1, v1
	v_cmp_ge_u32_e32 vcc, v3, v2
	v_add_u32_e32 v3, 1, v5
	s_nop 0
	v_cndmask_b32_e32 v1, v1, v4, vcc
	v_mul_lo_u32 v4, v2, v1
	v_add_u32_e32 v2, v4, v2
	v_sub_u32_e32 v4, v5, v4
	v_cmp_eq_u32_e32 vcc, 16, v4
	s_cbranch_vccz .Lefl_10
	buffer_wbl2 sc1
.Lefl_10:
	v_cmp_ne_u32_e32 vcc, v3, v2
	s_and_saveexec_b64 s[8:9], vcc
	s_xor_b64 s[8:9], exec, s[8:9]
	s_cbranch_execz .LBB0_1054
	s_waitcnt lgkmcnt(0)
	buffer_inv sc1
	v_mov_b32_e32 v0, 0x2000
	global_load_dword v0, v0, s[0:1] offset:1024 sc1
	s_add_u32 s14, s0, 0x2400
	s_addc_u32 s15, s1, 0
	s_waitcnt vmcnt(0)
	v_cmp_eq_u32_e32 vcc, v0, v1
	s_and_saveexec_b64 s[10:11], vcc
	s_cbranch_execz .LBB0_1053
	s_add_u32 s12, s54, 0x4200
	s_addc_u32 s13, s55, 0
	s_mov_b32 s3, 1
	s_mov_b64 s[16:17], 0
	v_mov_b32_e32 v0, 0
	s_branch .LBB0_1044
